# scan compute waves run at s_setprio 3 (loader waves stay at 0) for the duration of the scan loop
# speedup vs baseline: 1.0060x; 1.0034x over previous
.LBB0_496:
	s_and_b32 s54, s58, 1
	s_and_saveexec_b64 s[40:41], s[4:5]
	s_xor_b64 s[52:53], exec, s[40:41]
	s_cbranch_execz .LBB0_498
	s_setprio 3
	s_mov_b32 s11, s10
	s_mov_b32 s15, s14
	s_mov_b32 s35, s34
	s_mov_b32 s37, s36
	s_mov_b32 s43, s42
	s_mov_b32 s45, s44
	v_mov_b32_e32 v220, 0x1f000
	v_add_u32_e32 v221, 0x1f010, v23
	v_mov_b32_e32 v222, 1

.LBB0_506:
	s_setprio 0
	s_and_saveexec_b64 s[40:41], s[4:5]
	s_cbranch_execz .Lscan_flush_skip0
	v_add_f32_e32 v206, v144, v145
	v_add_f32_e32 v207, v146, v147
	v_cndmask_b32_e64 v208, v204, v205, s[10:11]
	v_cndmask_b32_e64 v209, v205, v204, s[10:11]
	v_cndmask_b32_e64 v210, v206, v207, s[10:11]
	v_cndmask_b32_e64 v211, v207, v206, s[10:11]
	v_add_f32_dpp v212, v209, v208 quad_perm:[1,0,3,2] row_mask:0xf bank_mask:0xf bound_ctrl:1
	s_nop 0
	v_add_f32_dpp v213, v211, v210 quad_perm:[1,0,3,2] row_mask:0xf bank_mask:0xf bound_ctrl:1
	v_cndmask_b32_e64 v214, v212, v213, s[14:15]
	v_cndmask_b32_e64 v215, v213, v212, s[14:15]
	s_nop 1
	v_add_f32_dpp v216, v215, v214 quad_perm:[2,3,0,1] row_mask:0xf bank_mask:0xf bound_ctrl:1
	s_nop 1
	v_add_f32_dpp v216, v216, v216 row_ror:8 row_mask:0xf bank_mask:0xf bound_ctrl:1
	s_nop 1
	v_add_f32_dpp v216, v216, v216 row_ror:4 row_mask:0xf bank_mask:0xf bound_ctrl:1
	v_cndmask_b32_e64 v28, v28, v216, s[44:45]
	v_add_co_u32_e32 v218, vcc, 0x4cfc000, v12
	s_nop 1
	v_addc_co_u32_e32 v219, vcc, 0, v13, vcc
	global_store_dword v[218:219], v28, off
